# M3 lru_tile<true>: all eight log-a/b row loads, the chunk-entry state and the four gate rows requested at the top of the tile (were 4+1+4 serial round trips)
# baseline (speedup 1.0000x reference)
; #define LAS __attribute__((address_space(3)))
; template <bool FULL> __device__ __forceinline__ void lru_tile(const Args& a, int l, int tile, LAS unsigned char* lds, int tid, int lane, int wave) {
;     ...
;     if constexpr (FULL) {
; #pragma unroll
;         for (int it = 0; it < 4; ++it) { const int ch = it * NTHR + tid, t = ch >> 5, c8 = ch & 31;
;             const u32x4 lv = *(const u32x4*)(Y + (size_t)(t0 + t) * DM + 768 + c8 * 8), bw = *(const u32x4*)(Y + (size_t)(t0 + t) * DM + 512 + c8 * 8);
;             float lf[8], bf[8]; unpack8(lv, lf); unpack8(bw, bf);
;             LAS f32x4* pa = (LAS f32x4*)(lds + OFF_LA + (t * 256 + c8 * 8) * 4); LAS f32x4* pb = (LAS f32x4*)(lds + OFF_LB + (t * 256 + c8 * 8) * 4);
;             pa[0] = (f32x4){__expf(lf[0]), __expf(lf[1]), __expf(lf[2]), __expf(lf[3])}; pa[1] = (f32x4){__expf(lf[4]), __expf(lf[5]), __expf(lf[6]), __expf(lf[7])};
;             pb[0] = (f32x4){bf[0], bf[1], bf[2], bf[3]}; pb[1] = (f32x4){bf[4], bf[5], bf[6], bf[7]}; }
;     ...
;     if (tid < 256) {
;         LAS float* A = (LAS float*)(lds + OFF_LA) + tid; LAS float* B = (LAS float*)(lds + OFF_LB) + tid;
;         float h = FULL ? HE[(size_t)tile * 256 + tid] : 0.f, P = 1.f;
.LBB0_1444:
	s_lshl_b32 s0, s26, 5
	s_and_b32 s0, s0, 0xe0
	s_ashr_i32 s1, s26, 3
	s_add_i32 s4, s0, s1
	v_readlane_b32 s0, v251, 16
	v_readlane_b32 s1, v251, 17
	s_and_b64 s[0:1], s[0:1], exec
	s_cselect_b32 s36, s4, s26
	v_mov_b32_e32 v24, v174
	s_lshl_b32 s27, s36, 6
	v_ashrrev_i32_e32 v10, 5, v24
	v_add_u32_e32 v12, s27, v10
	v_lshlrev_b32_e32 v0, 3, v24
	v_ashrrev_i32_e32 v13, 31, v12
	v_and_b32_e32 v2, 0xf8, v0
	v_lshlrev_b64 v[0:1], 11, v[12:13]
	v_lshl_add_u64 v[0:1], s[78:79], 0, v[0:1]
	v_lshlrev_b32_e32 v144, 1, v2
	v_lshl_add_u64 v[8:9], v[0:1], 0, v[144:145]
	v_lshlrev_b32_e32 v28, 2, v2
	s_ashr_i32 s37, s36, 31
	s_lshl_b64 s[6:7], s[36:37], 10
	v_readlane_b32 s16, v252, 54
	v_readlane_b32 s17, v252, 55
	s_add_u32 s6, s16, s6
	s_addc_u32 s7, s17, s7
	v_mov_b32_e32 v214, v24
	v_ashrrev_i32_e32 v215, 31, v24
	v_lshl_add_u64 v[216:217], v[214:215], 2, s[6:7]
	v_mul_lo_u32 v220, v12, s84
	v_mov_b32_e32 v221, 0
	v_add_u32_e32 v220, v220, v144
	v_add_u32_e32 v220, 0xd601400, v220
	v_lshl_add_u64 v[222:223], s[20:21], 0, v[220:221]
	v_add_u32_e32 v220, 0x16000, v220
	v_lshl_add_u64 v[224:225], s[20:21], 0, v[220:221]
	v_add_u32_e32 v220, 0x16000, v220
	v_lshl_add_u64 v[226:227], s[20:21], 0, v[220:221]
	v_add_u32_e32 v220, 0x16000, v220
	v_lshl_add_u64 v[228:229], s[20:21], 0, v[220:221]
	global_load_dword v218, v[216:217], off
	global_load_dwordx4 v[198:201], v[222:223], off
	global_load_dwordx4 v[202:205], v[224:225], off
	global_load_dwordx4 v[206:209], v[226:227], off
	global_load_dwordx4 v[210:213], v[228:229], off
	v_mov_b32_e32 v166, 0x8000
	v_mov_b32_e32 v167, 0
	v_lshl_add_u64 v[168:169], v[8:9], 0, v[166:167]
	v_lshl_add_u64 v[170:171], v[168:169], 0, v[166:167]
	v_lshl_add_u64 v[172:173], v[170:171], 0, v[166:167]
	global_load_dwordx4 v[126:129], v[8:9], off offset:1536
	global_load_dwordx4 v[130:133], v[8:9], off offset:1024
	global_load_dwordx4 v[134:137], v[168:169], off offset:1536
	global_load_dwordx4 v[138:141], v[168:169], off offset:1024
	global_load_dwordx4 v[150:153], v[170:171], off offset:1536
	global_load_dwordx4 v[154:157], v[170:171], off offset:1024
	global_load_dwordx4 v[158:161], v[172:173], off offset:1536
	global_load_dwordx4 v[162:165], v[172:173], off offset:1024
	s_waitcnt vmcnt(6)
	v_mov_b32_e32 v0, v126
	v_mov_b32_e32 v1, v127
	v_mov_b32_e32 v2, v128
	v_mov_b32_e32 v3, v129
	v_mov_b32_e32 v4, v130
	v_mov_b32_e32 v5, v131
	v_mov_b32_e32 v6, v132
	v_mov_b32_e32 v7, v133
	v_lshlrev_b32_e32 v13, 10, v10
	v_or_b32_e32 v10, v28, v13
	v_add_u32_e32 v22, 0, v10
	s_add_i32 s0, 0, 0x10000
	v_add_u32_e32 v10, s0, v10
	s_movk_i32 s1, 0x100
	v_cmp_gt_i32_e32 vcc, s1, v24
	v_lshlrev_b32_e32 v11, 16, v0
	v_and_b32_e32 v15, 0xffff0000, v0
	v_mul_f32_e32 v11, 0x3fb8aa3b, v11
	v_lshlrev_b32_e32 v16, 16, v1
	v_exp_f32_e32 v14, v11
	v_mul_f32_e32 v11, 0x3fb8aa3b, v15
	v_and_b32_e32 v17, 0xffff0000, v1
	v_exp_f32_e32 v15, v11
	v_mul_f32_e32 v11, 0x3fb8aa3b, v16
	v_exp_f32_e32 v16, v11
	v_mul_f32_e32 v11, 0x3fb8aa3b, v17
	v_exp_f32_e32 v17, v11
	v_lshlrev_b32_e32 v18, 16, v2
	v_and_b32_e32 v19, 0xffff0000, v2
	v_mul_f32_e32 v11, 0x3fb8aa3b, v18
	v_lshlrev_b32_e32 v20, 16, v3
	ds_write_b128 v22, v[14:17]
	v_exp_f32_e32 v14, v11
	v_mul_f32_e32 v11, 0x3fb8aa3b, v19
	v_and_b32_e32 v21, 0xffff0000, v3
	v_exp_f32_e32 v15, v11
	v_mul_f32_e32 v11, 0x3fb8aa3b, v20
	v_exp_f32_e32 v16, v11
	v_mul_f32_e32 v11, 0x3fb8aa3b, v21
	v_exp_f32_e32 v17, v11
	v_lshlrev_b32_e32 v0, 16, v4
	v_and_b32_e32 v1, 0xffff0000, v4
	v_lshlrev_b32_e32 v2, 16, v5
	v_and_b32_e32 v3, 0xffff0000, v5
	v_lshlrev_b32_e32 v4, 16, v6
	v_and_b32_e32 v5, 0xffff0000, v6
	v_lshlrev_b32_e32 v6, 16, v7
	v_and_b32_e32 v7, 0xffff0000, v7
	ds_write_b128 v22, v[14:17] offset:16
	ds_write_b128 v10, v[0:3]
	ds_write_b128 v10, v[4:7] offset:16
	v_add_u32_e32 v0, 0x200, v24
	v_ashrrev_i32_e32 v14, 5, v0
	v_add_u32_e32 v16, s27, v14
	v_ashrrev_i32_e32 v17, 31, v16
	v_lshlrev_b64 v[0:1], 11, v[16:17]
	v_lshl_add_u64 v[0:1], s[78:79], 0, v[0:1]
	v_lshl_add_u64 v[10:11], v[0:1], 0, v[144:145]
	s_waitcnt vmcnt(4)
	v_mov_b32_e32 v0, v134
	v_mov_b32_e32 v1, v135
	v_mov_b32_e32 v2, v136
	v_mov_b32_e32 v3, v137
	v_mov_b32_e32 v4, v138
	v_mov_b32_e32 v5, v139
	v_mov_b32_e32 v6, v140
	v_mov_b32_e32 v7, v141
	v_lshlrev_b32_e32 v17, 10, v14
	v_or_b32_e32 v14, v17, v28
	v_add_u32_e32 v27, 0, v14
	v_add_u32_e32 v14, s0, v14
	v_lshlrev_b32_e32 v15, 16, v0
	v_and_b32_e32 v19, 0xffff0000, v0
	v_mul_f32_e32 v15, 0x3fb8aa3b, v15
	v_lshlrev_b32_e32 v20, 16, v1
	v_exp_f32_e32 v18, v15
	v_mul_f32_e32 v15, 0x3fb8aa3b, v19
	v_and_b32_e32 v21, 0xffff0000, v1
	v_exp_f32_e32 v19, v15
	v_mul_f32_e32 v15, 0x3fb8aa3b, v20
	v_exp_f32_e32 v20, v15
	v_mul_f32_e32 v15, 0x3fb8aa3b, v21
	v_exp_f32_e32 v21, v15
	v_lshlrev_b32_e32 v22, 16, v2
	v_and_b32_e32 v23, 0xffff0000, v2
	v_mul_f32_e32 v15, 0x3fb8aa3b, v22
	v_lshlrev_b32_e32 v25, 16, v3
	ds_write_b128 v27, v[18:21]
	v_exp_f32_e32 v18, v15
	v_mul_f32_e32 v15, 0x3fb8aa3b, v23
	v_and_b32_e32 v26, 0xffff0000, v3
	v_exp_f32_e32 v19, v15
	v_mul_f32_e32 v15, 0x3fb8aa3b, v25
	v_exp_f32_e32 v20, v15
	v_mul_f32_e32 v15, 0x3fb8aa3b, v26
	v_exp_f32_e32 v21, v15
	v_lshlrev_b32_e32 v0, 16, v4
	v_and_b32_e32 v1, 0xffff0000, v4
	v_lshlrev_b32_e32 v2, 16, v5
	v_and_b32_e32 v3, 0xffff0000, v5
	v_lshlrev_b32_e32 v4, 16, v6
	v_and_b32_e32 v5, 0xffff0000, v6
	v_lshlrev_b32_e32 v6, 16, v7
	v_and_b32_e32 v7, 0xffff0000, v7
	ds_write_b128 v27, v[18:21] offset:16
	ds_write_b128 v14, v[0:3]
	ds_write_b128 v14, v[4:7] offset:16
	v_add_u32_e32 v0, 0x400, v24
	v_ashrrev_i32_e32 v20, 5, v0
	v_add_u32_e32 v18, s27, v20
	v_ashrrev_i32_e32 v19, 31, v18
	v_lshlrev_b64 v[0:1], 11, v[18:19]
	v_lshl_add_u64 v[0:1], s[78:79], 0, v[0:1]
	v_lshl_add_u64 v[14:15], v[0:1], 0, v[144:145]
	s_waitcnt vmcnt(2)
; #define LAS __attribute__((address_space(3)))
; template <bool FULL> __device__ __forceinline__ void lru_tile(const Args& a, int l, int tile, LAS unsigned char* lds, int tid, int lane, int wave) {
;     ...
;     if constexpr (FULL) {
; #pragma unroll
;         for (int it = 0; it < 4; ++it) { const int ch = it * NTHR + tid, t = ch >> 5, c8 = ch & 31;
;             const u32x4 lv = *(const u32x4*)(Y + (size_t)(t0 + t) * DM + 768 + c8 * 8), bw = *(const u32x4*)(Y + (size_t)(t0 + t) * DM + 512 + c8 * 8);
;             float lf[8], bf[8]; unpack8(lv, lf); unpack8(bw, bf);
;             LAS f32x4* pa = (LAS f32x4*)(lds + OFF_LA + (t * 256 + c8 * 8) * 4); LAS f32x4* pb = (LAS f32x4*)(lds + OFF_LB + (t * 256 + c8 * 8) * 4);
;             pa[0] = (f32x4){__expf(lf[0]), __expf(lf[1]), __expf(lf[2]), __expf(lf[3])}; pa[1] = (f32x4){__expf(lf[4]), __expf(lf[5]), __expf(lf[6]), __expf(lf[7])};
;             pb[0] = (f32x4){bf[0], bf[1], bf[2], bf[3]}; pb[1] = (f32x4){bf[4], bf[5], bf[6], bf[7]}; }
;     ...
;     if (tid < 256) {
;         LAS float* A = (LAS float*)(lds + OFF_LA) + tid; LAS float* B = (LAS float*)(lds + OFF_LB) + tid;
;         float h = FULL ? HE[(size_t)tile * 256 + tid] : 0.f, P = 1.f;
;         for (int tb = 0; tb < 64; tb += 16) {
;             float av_[16], bv_[16];
; #pragma unroll
;             for (int j = 0; j < 16; ++j) { av_[j] = A[(tb + j) * 256]; bv_[j] = B[(tb + j) * 256]; }
; #pragma unroll
;             for (int j = 0; j < 16; ++j) { h = fmaf(av_[j], h, bv_[j]); if (FULL) bv_[j] = h; else P *= av_[j]; }
	v_mov_b32_e32 v0, v150
	v_mov_b32_e32 v1, v151
	v_mov_b32_e32 v2, v152
	v_mov_b32_e32 v3, v153
	v_mov_b32_e32 v4, v154
	v_mov_b32_e32 v5, v155
	v_mov_b32_e32 v6, v156
	v_mov_b32_e32 v7, v157
	v_lshlrev_b32_e32 v19, 10, v20
	v_or_b32_e32 v20, v19, v28
	v_add_u32_e32 v31, 0, v20
	v_add_u32_e32 v32, s0, v20
	v_lshlrev_b32_e32 v21, 16, v0
	v_and_b32_e32 v22, 0xffff0000, v0
	v_lshlrev_b32_e32 v23, 16, v1
	v_and_b32_e32 v25, 0xffff0000, v1
	v_mul_f32_e32 v20, 0x3fb8aa3b, v21
	v_mul_f32_e32 v21, 0x3fb8aa3b, v22
	v_mul_f32_e32 v22, 0x3fb8aa3b, v23
	v_mul_f32_e32 v23, 0x3fb8aa3b, v25
	v_exp_f32_e32 v20, v20
	v_exp_f32_e32 v21, v21
	v_exp_f32_e32 v22, v22
	v_exp_f32_e32 v23, v23
	v_lshlrev_b32_e32 v26, 16, v2
	v_and_b32_e32 v27, 0xffff0000, v2
	v_lshlrev_b32_e32 v29, 16, v3
	v_and_b32_e32 v30, 0xffff0000, v3
	ds_write_b128 v31, v[20:23]
	v_mul_f32_e32 v20, 0x3fb8aa3b, v26
	v_mul_f32_e32 v21, 0x3fb8aa3b, v27
	v_mul_f32_e32 v22, 0x3fb8aa3b, v29
	v_mul_f32_e32 v23, 0x3fb8aa3b, v30
	v_exp_f32_e32 v20, v20
	v_exp_f32_e32 v21, v21
	v_exp_f32_e32 v22, v22
	v_exp_f32_e32 v23, v23
	v_lshlrev_b32_e32 v0, 16, v4
	v_and_b32_e32 v1, 0xffff0000, v4
	v_lshlrev_b32_e32 v2, 16, v5
	v_and_b32_e32 v3, 0xffff0000, v5
	v_lshlrev_b32_e32 v4, 16, v6
	v_and_b32_e32 v5, 0xffff0000, v6
	v_lshlrev_b32_e32 v6, 16, v7
	v_and_b32_e32 v7, 0xffff0000, v7
	ds_write_b128 v31, v[20:23] offset:16
	ds_write_b128 v32, v[0:3]
	ds_write_b128 v32, v[4:7] offset:16
	v_add_u32_e32 v0, 0x600, v24
	v_ashrrev_i32_e32 v25, 5, v0
	v_add_u32_e32 v22, s27, v25
	v_ashrrev_i32_e32 v23, 31, v22
	v_lshlrev_b64 v[0:1], 11, v[22:23]
	v_lshl_add_u64 v[0:1], s[78:79], 0, v[0:1]
	v_lshl_add_u64 v[20:21], v[0:1], 0, v[144:145]
	s_waitcnt vmcnt(0)
	v_mov_b32_e32 v4, v158
	v_mov_b32_e32 v5, v159
	v_mov_b32_e32 v6, v160
	v_mov_b32_e32 v7, v161
	v_mov_b32_e32 v0, v162
	v_mov_b32_e32 v1, v163
	v_mov_b32_e32 v2, v164
	v_mov_b32_e32 v3, v165
	v_lshlrev_b32_e32 v23, 10, v25
	v_or_b32_e32 v25, v23, v28
	v_add_u32_e32 v38, 0, v25
	v_add_u32_e32 v25, s0, v25
	v_lshlrev_b32_e32 v26, 16, v4
	v_and_b32_e32 v27, 0xffff0000, v4
	v_mul_f32_e32 v26, 0x3fb8aa3b, v26
	v_lshlrev_b32_e32 v29, 16, v5
	v_exp_f32_e32 v30, v26
	v_mul_f32_e32 v26, 0x3fb8aa3b, v27
	v_and_b32_e32 v33, 0xffff0000, v5
	v_exp_f32_e32 v31, v26
	v_mul_f32_e32 v26, 0x3fb8aa3b, v29
	v_exp_f32_e32 v32, v26
	v_mul_f32_e32 v26, 0x3fb8aa3b, v33
	v_exp_f32_e32 v33, v26
	v_lshlrev_b32_e32 v34, 16, v6
	v_and_b32_e32 v35, 0xffff0000, v6
	v_mul_f32_e32 v26, 0x3fb8aa3b, v34
	v_lshlrev_b32_e32 v36, 16, v7
	ds_write_b128 v38, v[30:33]
	v_exp_f32_e32 v30, v26
	v_mul_f32_e32 v26, 0x3fb8aa3b, v35
	v_and_b32_e32 v37, 0xffff0000, v7
	v_exp_f32_e32 v31, v26
	v_mul_f32_e32 v26, 0x3fb8aa3b, v36
	v_exp_f32_e32 v32, v26
	v_mul_f32_e32 v26, 0x3fb8aa3b, v37
	v_exp_f32_e32 v33, v26
	v_lshlrev_b32_e32 v4, 16, v0
	v_and_b32_e32 v5, 0xffff0000, v0
	v_lshlrev_b32_e32 v6, 16, v1
	v_and_b32_e32 v7, 0xffff0000, v1
	v_lshlrev_b32_e32 v0, 16, v2
	v_and_b32_e32 v1, 0xffff0000, v2
	v_lshlrev_b32_e32 v2, 16, v3
	v_and_b32_e32 v3, 0xffff0000, v3
	ds_write_b128 v38, v[30:33] offset:16
	ds_write_b128 v25, v[4:7]
	ds_write_b128 v25, v[0:3] offset:16
	s_waitcnt lgkmcnt(0)
	s_barrier
	s_and_saveexec_b64 s[4:5], vcc
	s_cbranch_execz .LBB0_1446
	s_ashr_i32 s37, s36, 31
	s_lshl_b64 s[6:7], s[36:37], 10
	v_readlane_b32 s16, v252, 54
	v_readlane_b32 s17, v252, 55
	s_add_u32 s6, s16, s6
	v_ashrrev_i32_e32 v25, 31, v24
	s_addc_u32 s7, s17, s7
	v_lshl_add_u64 v[0:1], v[24:25], 2, s[6:7]
	v_mov_b32_e32 v31, v218
	v_lshl_add_u32 v30, v24, 2, 0
	v_add_u32_e32 v29, 0x10000, v30
	ds_read2st64_b32 v[0:1], v30 offset1:4
	ds_read2st64_b32 v[2:3], v29 offset1:4
	ds_read2st64_b32 v[4:5], v30 offset0:8 offset1:12
	ds_read2st64_b32 v[6:7], v29 offset0:8 offset1:12
	ds_read2st64_b32 v[24:25], v30 offset0:16 offset1:20
	ds_read2st64_b32 v[26:27], v29 offset0:16 offset1:20
	ds_read2st64_b32 v[32:33], v30 offset0:24 offset1:28
	ds_read2st64_b32 v[34:35], v29 offset0:24 offset1:28
	ds_read2st64_b32 v[36:37], v30 offset0:32 offset1:36
	ds_read2st64_b32 v[38:39], v29 offset0:32 offset1:36
	ds_read2st64_b32 v[40:41], v30 offset0:40 offset1:44
	ds_read2st64_b32 v[42:43], v29 offset0:40 offset1:44
	ds_read2st64_b32 v[44:45], v30 offset0:48 offset1:52
	ds_read2st64_b32 v[46:47], v29 offset0:48 offset1:52
	ds_read2st64_b32 v[48:49], v30 offset0:56 offset1:60
	ds_read2st64_b32 v[50:51], v29 offset0:56 offset1:60
	s_waitcnt lgkmcnt(14)
	v_fma_f32 v0, v0, v31, v2
	v_fmac_f32_e32 v3, v1, v0
	s_waitcnt lgkmcnt(12)
	v_fma_f32 v1, v4, v3, v6
	v_fmac_f32_e32 v7, v5, v1
	s_waitcnt lgkmcnt(10)
	v_fma_f32 v2, v24, v7, v26
	v_fmac_f32_e32 v27, v25, v2
	s_waitcnt lgkmcnt(8)
	v_fma_f32 v4, v32, v27, v34
	v_fmac_f32_e32 v35, v33, v4
	s_waitcnt lgkmcnt(6)
	v_fma_f32 v5, v36, v35, v38
	v_fmac_f32_e32 v39, v37, v5
	s_waitcnt lgkmcnt(4)
	v_fma_f32 v6, v40, v39, v42
	v_fmac_f32_e32 v43, v41, v6
	s_waitcnt lgkmcnt(2)
	v_fma_f32 v24, v44, v43, v46
	v_fmac_f32_e32 v47, v45, v24
	s_waitcnt lgkmcnt(0)
; template <bool FULL> __device__ __forceinline__ void lru_tile(const Args& a, int l, int tile, LAS unsigned char* lds, int tid, int lane, int wave) {
;     ...
;         for (int tb = 0; tb < 64; tb += 16) {
;             float av_[16], bv_[16];
; #pragma unroll
;             for (int j = 0; j < 16; ++j) { av_[j] = A[(tb + j) * 256]; bv_[j] = B[(tb + j) * 256]; }
; #pragma unroll
;             for (int j = 0; j < 16; ++j) { h = fmaf(av_[j], h, bv_[j]); if (FULL) bv_[j] = h; else P *= av_[j]; }
;             if (FULL) {
; #pragma unroll
;                 for (int j = 0; j < 16; ++j) B[(tb + j) * 256] = bv_[j];
;             }
	v_fma_f32 v25, v48, v47, v50
	v_fmac_f32_e32 v51, v49, v25
	ds_write2st64_b32 v29, v0, v3 offset1:4
	ds_write2st64_b32 v29, v1, v7 offset0:8 offset1:12
	ds_write2st64_b32 v29, v2, v27 offset0:16 offset1:20
	ds_write2st64_b32 v29, v4, v35 offset0:24 offset1:28
	ds_write2st64_b32 v29, v5, v39 offset0:32 offset1:36
	ds_write2st64_b32 v29, v6, v43 offset0:40 offset1:44
	ds_write2st64_b32 v29, v24, v47 offset0:48 offset1:52
	ds_write2st64_b32 v29, v25, v51 offset0:56 offset1:60
	ds_read2st64_b32 v[0:1], v30 offset0:64 offset1:68
	ds_read2st64_b32 v[2:3], v29 offset0:64 offset1:68
	ds_read2st64_b32 v[4:5], v30 offset0:72 offset1:76
	ds_read2st64_b32 v[6:7], v29 offset0:72 offset1:76
	ds_read2st64_b32 v[24:25], v30 offset0:80 offset1:84
	ds_read2st64_b32 v[26:27], v29 offset0:80 offset1:84
	ds_read2st64_b32 v[32:33], v30 offset0:88 offset1:92
	ds_read2st64_b32 v[34:35], v29 offset0:88 offset1:92
	ds_read2st64_b32 v[36:37], v30 offset0:96 offset1:100
	ds_read2st64_b32 v[38:39], v29 offset0:96 offset1:100
	ds_read2st64_b32 v[40:41], v30 offset0:104 offset1:108
	ds_read2st64_b32 v[42:43], v29 offset0:104 offset1:108
	ds_read2st64_b32 v[44:45], v30 offset0:112 offset1:116
	ds_read2st64_b32 v[46:47], v29 offset0:112 offset1:116
	ds_read2st64_b32 v[48:49], v30 offset0:120 offset1:124
	ds_read2st64_b32 v[52:53], v29 offset0:120 offset1:124
	s_waitcnt lgkmcnt(14)
	v_fma_f32 v0, v0, v51, v2
	v_fmac_f32_e32 v3, v1, v0
	s_waitcnt lgkmcnt(12)
	v_fma_f32 v1, v4, v3, v6
	v_fmac_f32_e32 v7, v5, v1
	s_waitcnt lgkmcnt(10)
	v_fma_f32 v2, v24, v7, v26
	v_fmac_f32_e32 v27, v25, v2
	s_waitcnt lgkmcnt(8)
	v_fma_f32 v4, v32, v27, v34
	v_fmac_f32_e32 v35, v33, v4
	s_waitcnt lgkmcnt(6)
	v_fma_f32 v5, v36, v35, v38
	v_fmac_f32_e32 v39, v37, v5
	s_waitcnt lgkmcnt(4)
	v_fma_f32 v6, v40, v39, v42
	v_fmac_f32_e32 v43, v41, v6
	s_waitcnt lgkmcnt(2)
	v_fma_f32 v24, v44, v43, v46
	v_fmac_f32_e32 v47, v45, v24
	s_waitcnt lgkmcnt(0)
	v_fma_f32 v25, v48, v47, v52
	v_fmac_f32_e32 v53, v49, v25
	ds_write2st64_b32 v29, v0, v3 offset0:64 offset1:68
	ds_write2st64_b32 v29, v1, v7 offset0:72 offset1:76
	ds_write2st64_b32 v29, v2, v27 offset0:80 offset1:84
	ds_write2st64_b32 v29, v4, v35 offset0:88 offset1:92
	ds_write2st64_b32 v29, v5, v39 offset0:96 offset1:100
	ds_write2st64_b32 v29, v6, v43 offset0:104 offset1:108
	ds_write2st64_b32 v29, v24, v47 offset0:112 offset1:116
	ds_write2st64_b32 v29, v25, v53 offset0:120 offset1:124
	ds_read2st64_b32 v[2:3], v30 offset0:128 offset1:132
	ds_read2st64_b32 v[4:5], v29 offset0:128 offset1:132
	ds_read2st64_b32 v[6:7], v30 offset0:136 offset1:140
	ds_read2st64_b32 v[24:25], v29 offset0:136 offset1:140
	ds_read2st64_b32 v[26:27], v30 offset0:144 offset1:148
	ds_read2st64_b32 v[32:33], v29 offset0:144 offset1:148
	ds_read2st64_b32 v[34:35], v30 offset0:152 offset1:156
	ds_read2st64_b32 v[36:37], v29 offset0:152 offset1:156
	ds_read2st64_b32 v[38:39], v30 offset0:160 offset1:164
	ds_read2st64_b32 v[40:41], v29 offset0:160 offset1:164
	ds_read2st64_b32 v[42:43], v30 offset0:168 offset1:172
	ds_read2st64_b32 v[44:45], v29 offset0:168 offset1:172
	ds_read2st64_b32 v[46:47], v30 offset0:176 offset1:180
	ds_read2st64_b32 v[48:49], v29 offset0:176 offset1:180
	ds_read2st64_b32 v[50:51], v30 offset0:184 offset1:188
	ds_read2st64_b32 v[0:1], v29 offset0:184 offset1:188
	s_waitcnt lgkmcnt(14)
	v_fma_f32 v2, v2, v53, v4
	v_fmac_f32_e32 v5, v3, v2
	s_waitcnt lgkmcnt(12)
	v_fma_f32 v3, v6, v5, v24
	v_fmac_f32_e32 v25, v7, v3
	s_waitcnt lgkmcnt(10)
	v_fma_f32 v4, v26, v25, v32
	v_fmac_f32_e32 v33, v27, v4
	s_waitcnt lgkmcnt(8)
	v_fma_f32 v6, v34, v33, v36
	v_fmac_f32_e32 v37, v35, v6
	s_waitcnt lgkmcnt(6)
	v_fma_f32 v7, v38, v37, v40
	v_fmac_f32_e32 v41, v39, v7
	s_waitcnt lgkmcnt(4)
	v_fma_f32 v24, v42, v41, v44
	v_fmac_f32_e32 v45, v43, v24
	s_waitcnt lgkmcnt(2)
	v_fma_f32 v26, v46, v45, v48
	v_fmac_f32_e32 v49, v47, v26
	s_waitcnt lgkmcnt(0)
	v_fma_f32 v0, v50, v49, v0
	v_fmac_f32_e32 v1, v51, v0
	ds_write2st64_b32 v29, v2, v5 offset0:128 offset1:132
	ds_write2st64_b32 v29, v3, v25 offset0:136 offset1:140
	ds_write2st64_b32 v29, v4, v33 offset0:144 offset1:148
	ds_write2st64_b32 v29, v6, v37 offset0:152 offset1:156
	ds_write2st64_b32 v29, v7, v41 offset0:160 offset1:164
	ds_write2st64_b32 v29, v24, v45 offset0:168 offset1:172
	ds_write2st64_b32 v29, v26, v49 offset0:176 offset1:180
	ds_write2st64_b32 v29, v0, v1 offset0:184 offset1:188
	ds_read2st64_b32 v[6:7], v30 offset0:192 offset1:196
	ds_read2st64_b32 v[2:3], v29 offset0:192 offset1:196
	ds_read2st64_b32 v[24:25], v30 offset0:200 offset1:204
	ds_read2st64_b32 v[4:5], v29 offset0:200 offset1:204
	ds_read2st64_b32 v[26:27], v30 offset0:208 offset1:212
	ds_read2st64_b32 v[32:33], v29 offset0:208 offset1:212
	ds_read2st64_b32 v[34:35], v30 offset0:216 offset1:220
	ds_read2st64_b32 v[36:37], v29 offset0:216 offset1:220
	ds_read2st64_b32 v[38:39], v30 offset0:224 offset1:228
	ds_read2st64_b32 v[40:41], v29 offset0:224 offset1:228
	ds_read2st64_b32 v[42:43], v30 offset0:232 offset1:236
	ds_read2st64_b32 v[44:45], v29 offset0:232 offset1:236
	ds_read2st64_b32 v[46:47], v30 offset0:240 offset1:244
	ds_read2st64_b32 v[48:49], v29 offset0:240 offset1:244
	ds_read2st64_b32 v[30:31], v30 offset0:248 offset1:252
	ds_read2st64_b32 v[50:51], v29 offset0:248 offset1:252
	s_waitcnt lgkmcnt(14)
	v_fma_f32 v0, v6, v1, v2
	v_fmac_f32_e32 v3, v7, v0
	s_waitcnt lgkmcnt(12)
	v_fma_f32 v1, v24, v3, v4
	v_fmac_f32_e32 v5, v25, v1
	s_waitcnt lgkmcnt(10)
	v_fma_f32 v2, v26, v5, v32
	v_fmac_f32_e32 v33, v27, v2
	s_waitcnt lgkmcnt(8)
	v_fma_f32 v4, v34, v33, v36
	v_fmac_f32_e32 v37, v35, v4
	s_waitcnt lgkmcnt(6)
	v_fma_f32 v6, v38, v37, v40
	v_fmac_f32_e32 v41, v39, v6
	s_waitcnt lgkmcnt(4)
	v_fma_f32 v7, v42, v41, v44
	v_fmac_f32_e32 v45, v43, v7
	s_waitcnt lgkmcnt(2)
	v_fma_f32 v24, v46, v45, v48
	v_fmac_f32_e32 v49, v47, v24
	s_waitcnt lgkmcnt(0)
	v_fma_f32 v25, v30, v49, v50
	v_fmac_f32_e32 v51, v31, v25
	ds_write2st64_b32 v29, v0, v3 offset0:192 offset1:196
	ds_write2st64_b32 v29, v1, v5 offset0:200 offset1:204
	ds_write2st64_b32 v29, v2, v33 offset0:208 offset1:212
	ds_write2st64_b32 v29, v4, v37 offset0:216 offset1:220
	ds_write2st64_b32 v29, v6, v41 offset0:224 offset1:228
	ds_write2st64_b32 v29, v7, v45 offset0:232 offset1:236
	ds_write2st64_b32 v29, v24, v49 offset0:240 offset1:244
	ds_write2st64_b32 v29, v25, v51 offset0:248 offset1:252
; #define LAS __attribute__((address_space(3)))
; __device__ __forceinline__ unsigned pk2(float lo, float hi) { return pg8::cvt_pk_bf16(lo, hi); }
; template <bool FULL> __device__ __forceinline__ void lru_tile(const Args& a, int l, int tile, LAS unsigned char* lds, int tid, int lane, int wave) {
;     ...
;     if (FULL) {
; #pragma unroll
;         for (int it = 0; it < 4; ++it) {
;             const int ch = it * NTHR + tid, t = ch >> 5, c8 = ch & 31;
;             const LAS f32x4* hp = (const LAS f32x4*)(lds + OFF_LB + (t * 256 + c8 * 8) * 4); const f32x4 h0 = hp[0], h1 = hp[1];
;             const u32x4 gv = *(const u32x4*)(Z + (size_t)(t0 + t) * IW + 2560 + c8 * 8); float g[8]; unpack8(gv, g);
;             float o[8] = {h0.x * g[0], h0.y * g[1], h0.z * g[2], h0.w * g[3], h1.x * g[4], h1.y * g[5], h1.z * g[6], h1.w * g[7]};
;             float ss = 0.f;
; #pragma unroll
;             for (int i = 0; i < 8; ++i) ss += o[i] * o[i];
; #pragma unroll
;             for (int s = 1; s < 32; s <<= 1) ss += __shfl_xor(ss, s);
;             const float rstd = rsqrtf(ss * (1.0f / 256.0f) + EPS);
;             u32x4 w; w.x = pk2(o[0] * rstd, o[1] * rstd); w.y = pk2(o[2] * rstd, o[3] * rstd); w.z = pk2(o[4] * rstd, o[5] * rstd); w.w = pk2(o[6] * rstd, o[7] * rstd);
;             *(u32x4*)(Y + (size_t)(t0 + t) * DM + 768 + c8 * 8) = w;
.LBB0_1446:
	s_or_b64 exec, exec, s[4:5]
	v_mov_b64_e32 v[0:1], s[20:21]
	v_mad_i64_i32 v[2:3], s[4:5], v12, s84, v[0:1]
	v_lshl_add_u64 v[2:3], v[2:3], 0, v[144:145]
	s_mov_b32 s4, 0xd601000
	v_add_co_u32_e32 v2, vcc, s4, v2
	s_waitcnt lgkmcnt(0)
	s_nop 0
	v_addc_co_u32_e32 v3, vcc, 0, v3, vcc
	s_barrier
	s_nop 1
	v_mov_b32_e32 v2, v198
	v_mov_b32_e32 v3, v199
	v_mov_b32_e32 v4, v200
	v_mov_b32_e32 v5, v201
	v_add_u32_e32 v32, s0, v28
	v_and_b32_e32 v6, 64, v175
	v_add_u32_e32 v62, 64, v6
	v_add_u32_e32 v6, v32, v13
	ds_read_b128 v[24:27], v6
	ds_read_b128 v[28:31], v6 offset:16
	v_xor_b32_e32 v7, 1, v175
	v_cmp_lt_i32_e32 vcc, v7, v62
	v_mov_b32_e32 v126, v174
	s_and_b32 s24, s36, 1
	v_cndmask_b32_e32 v6, v175, v7, vcc
	v_lshlrev_b32_e32 v33, 2, v6
	v_and_b32_e32 v35, 0xffff0000, v2
	v_lshlrev_b32_e32 v34, 16, v2
	v_and_b32_e32 v7, 0xffff0000, v3
	v_lshlrev_b32_e32 v6, 16, v3
	v_and_b32_e32 v3, 0xffff0000, v4
	v_lshlrev_b32_e32 v2, 16, v4
	s_waitcnt lgkmcnt(1)
	v_mul_f32_e32 v35, v25, v35
	v_and_b32_e32 v13, 0xffff0000, v5
	v_lshlrev_b32_e32 v12, 16, v5
	v_mul_f32_e32 v34, v24, v34
	v_pk_mul_f32 v[4:5], v[26:27], v[6:7]
	s_waitcnt lgkmcnt(0)
	v_pk_mul_f32 v[2:3], v[28:29], v[2:3]
	v_mul_f32_e32 v28, v35, v35
	v_pk_mul_f32 v[6:7], v[30:31], v[12:13]
	v_pk_mul_f32 v[12:13], v[4:5], v[4:5]
	v_fmac_f32_e32 v28, v34, v34
	v_add_f32_e32 v12, v12, v28
	v_pk_mul_f32 v[24:25], v[2:3], v[2:3]
	v_add_f32_e32 v12, v13, v12
	v_add_f32_e32 v12, v24, v12
	v_pk_mul_f32 v[26:27], v[6:7], v[6:7]
	v_add_f32_e32 v12, v25, v12
	v_add_f32_e32 v12, v26, v12
	v_add_f32_e32 v12, v27, v12
	ds_bpermute_b32 v13, v33, v12
	v_xor_b32_e32 v24, 2, v175
	v_cmp_lt_i32_e32 vcc, v24, v62
	s_waitcnt lgkmcnt(0)
	v_add_f32_e32 v12, v12, v13
	v_cndmask_b32_e32 v24, v175, v24, vcc
	v_lshlrev_b32_e32 v28, 2, v24
	ds_bpermute_b32 v13, v28, v12
	v_xor_b32_e32 v24, 4, v175
	v_cmp_lt_i32_e32 vcc, v24, v62
	s_waitcnt lgkmcnt(0)
	v_add_f32_e32 v12, v12, v13
	v_cndmask_b32_e32 v24, v175, v24, vcc
	v_lshlrev_b32_e32 v29, 2, v24
	ds_bpermute_b32 v13, v29, v12
	v_xor_b32_e32 v24, 8, v175
	v_cmp_lt_i32_e32 vcc, v24, v62
	s_waitcnt lgkmcnt(0)
	v_add_f32_e32 v12, v12, v13
	v_cndmask_b32_e32 v24, v175, v24, vcc
	v_lshlrev_b32_e32 v30, 2, v24
	ds_bpermute_b32 v13, v30, v12
	v_xor_b32_e32 v24, 16, v175
	v_cmp_lt_i32_e32 vcc, v24, v62
	s_nop 1
	v_cndmask_b32_e32 v24, v175, v24, vcc
	v_lshlrev_b32_e32 v124, 2, v24
	s_waitcnt lgkmcnt(0)
	v_add_f32_e32 v24, v12, v13
	ds_bpermute_b32 v25, v124, v24
	v_mad_i64_i32 v[12:13], s[0:1], v16, s84, v[0:1]
	v_lshl_add_u64 v[12:13], v[12:13], 0, v[144:145]
	v_add_co_u32_e64 v12, s[38:39], s4, v12
	s_waitcnt lgkmcnt(0)
	v_add_f32_e32 v16, v24, v25
	v_fmamk_f32 v16, v16, 0x3b800000, v179
	v_mul_f32_e32 v24, 0x4b800000, v16
	v_cmp_gt_f32_e32 vcc, s33, v16
	v_addc_co_u32_e64 v13, s[38:39], 0, v13, s[38:39]
	s_nop 0
	v_cndmask_b32_e32 v16, v16, v24, vcc
	v_rsq_f32_e32 v16, v16
	s_nop 0
	v_mul_f32_e32 v24, 0x45800000, v16
	v_cndmask_b32_e32 v16, v16, v24, vcc
	v_mul_f32_e32 v4, v4, v16
	v_mul_f32_e32 v5, v5, v16
	v_mul_f32_e32 v24, v34, v16
	v_mul_f32_e32 v25, v35, v16
	v_mul_f32_e32 v26, v2, v16
	v_mul_f32_e32 v27, v3, v16
	v_mul_f32_e32 v6, v6, v16
	v_mul_f32_e32 v7, v7, v16
	v_cvt_pk_bf16_f32 v2, v24, v25
	v_cvt_pk_bf16_f32 v3, v4, v5
	v_cvt_pk_bf16_f32 v4, v26, v27
	v_cvt_pk_bf16_f32 v5, v6, v7
	global_store_dwordx4 v[8:9], v[2:5], off offset:1536
	s_nop 1
	v_mov_b32_e32 v2, v202
	v_mov_b32_e32 v3, v203
	v_mov_b32_e32 v4, v204
	v_mov_b32_e32 v5, v205
	v_add_u32_e32 v12, v32, v17
	ds_read_b128 v[6:9], v12
	ds_read_b128 v[24:27], v12 offset:16
	v_and_b32_e32 v34, 0xffff0000, v2
	v_lshlrev_b32_e32 v31, 16, v2
	v_and_b32_e32 v13, 0xffff0000, v3
	v_lshlrev_b32_e32 v12, 16, v3
	v_and_b32_e32 v3, 0xffff0000, v4
	v_lshlrev_b32_e32 v2, 16, v4
	s_waitcnt lgkmcnt(1)
	v_mul_f32_e32 v34, v7, v34
	v_and_b32_e32 v17, 0xffff0000, v5
	v_lshlrev_b32_e32 v16, 16, v5
	v_mul_f32_e32 v31, v6, v31
	v_pk_mul_f32 v[4:5], v[8:9], v[12:13]
	s_waitcnt lgkmcnt(0)
	v_pk_mul_f32 v[2:3], v[24:25], v[2:3]
	v_mul_f32_e32 v24, v34, v34
	v_pk_mul_f32 v[8:9], v[4:5], v[4:5]
	v_fmac_f32_e32 v24, v31, v31
	v_add_f32_e32 v8, v8, v24
	v_pk_mul_f32 v[12:13], v[2:3], v[2:3]
	v_add_f32_e32 v8, v9, v8
	v_pk_mul_f32 v[6:7], v[26:27], v[16:17]
	v_add_f32_e32 v8, v12, v8
	v_pk_mul_f32 v[16:17], v[6:7], v[6:7]
	v_add_f32_e32 v8, v13, v8
	v_add_f32_e32 v8, v16, v8
	v_add_f32_e32 v8, v17, v8
	ds_bpermute_b32 v9, v33, v8
	s_waitcnt lgkmcnt(0)
	v_add_f32_e32 v8, v8, v9
	ds_bpermute_b32 v9, v28, v8
	s_waitcnt lgkmcnt(0)
	v_add_f32_e32 v8, v8, v9
	ds_bpermute_b32 v9, v29, v8
	s_waitcnt lgkmcnt(0)
	v_add_f32_e32 v8, v8, v9
	ds_bpermute_b32 v9, v30, v8
	s_waitcnt lgkmcnt(0)
	v_add_f32_e32 v12, v8, v9
	ds_bpermute_b32 v13, v124, v12
	v_mad_i64_i32 v[8:9], s[0:1], v18, s84, v[0:1]
	v_lshl_add_u64 v[8:9], v[8:9], 0, v[144:145]
	v_add_co_u32_e64 v8, s[38:39], s4, v8
	s_waitcnt lgkmcnt(0)
	v_add_f32_e32 v12, v12, v13
	v_fmamk_f32 v12, v12, 0x3b800000, v179
	v_mul_f32_e32 v13, 0x4b800000, v12
	v_cmp_gt_f32_e32 vcc, s33, v12
	v_addc_co_u32_e64 v9, s[38:39], 0, v9, s[38:39]
	s_nop 0
	v_cndmask_b32_e32 v12, v12, v13, vcc
	v_rsq_f32_e32 v12, v12
	v_mad_i64_i32 v[0:1], s[0:1], v22, s84, v[0:1]
	v_lshl_add_u64 v[0:1], v[0:1], 0, v[144:145]
	v_mul_f32_e32 v13, 0x45800000, v12
	v_cndmask_b32_e32 v12, v12, v13, vcc
	v_mul_f32_e32 v4, v4, v12
	v_mul_f32_e32 v5, v5, v12
	v_mul_f32_e32 v13, v31, v12
	v_mul_f32_e32 v16, v34, v12
	v_mul_f32_e32 v17, v2, v12
	v_mul_f32_e32 v18, v3, v12
	v_mul_f32_e32 v6, v6, v12
	v_mul_f32_e32 v7, v7, v12
	v_cvt_pk_bf16_f32 v2, v13, v16
	v_cvt_pk_bf16_f32 v3, v4, v5
	v_cvt_pk_bf16_f32 v4, v17, v18
	v_cvt_pk_bf16_f32 v5, v6, v7
	global_store_dwordx4 v[10:11], v[2:5], off offset:1536
	s_nop 1
	v_mov_b32_e32 v2, v206
	v_mov_b32_e32 v3, v207
	v_mov_b32_e32 v4, v208
	v_mov_b32_e32 v5, v209
	v_add_u32_e32 v10, v32, v19
	ds_read_b128 v[6:9], v10
	ds_read_b128 v[10:13], v10 offset:16
	s_ashr_i32 s0, s36, 7
	s_bfe_u32 s1, s36, 0x60001
	s_lshl_b32 s5, s1, 7
	v_and_b32_e32 v25, 0xffff0000, v2
	v_lshlrev_b32_e32 v24, 16, v2
	v_and_b32_e32 v17, 0xffff0000, v3
	v_lshlrev_b32_e32 v16, 16, v3
	s_waitcnt lgkmcnt(1)
; #define LAS __attribute__((address_space(3)))
; __device__ __forceinline__ unsigned pk2(float lo, float hi) { return pg8::cvt_pk_bf16(lo, hi); }
; template <bool FULL> __device__ __forceinline__ void lru_tile(const Args& a, int l, int tile, LAS unsigned char* lds, int tid, int lane, int wave) {
;     ...
;     if (FULL) {
; #pragma unroll
;         for (int it = 0; it < 4; ++it) {
;             const int ch = it * NTHR + tid, t = ch >> 5, c8 = ch & 31;
;             const LAS f32x4* hp = (const LAS f32x4*)(lds + OFF_LB + (t * 256 + c8 * 8) * 4); const f32x4 h0 = hp[0], h1 = hp[1];
;             const u32x4 gv = *(const u32x4*)(Z + (size_t)(t0 + t) * IW + 2560 + c8 * 8); float g[8]; unpack8(gv, g);
;             float o[8] = {h0.x * g[0], h0.y * g[1], h0.z * g[2], h0.w * g[3], h1.x * g[4], h1.y * g[5], h1.z * g[6], h1.w * g[7]};
;             float ss = 0.f;
; #pragma unroll
;             for (int i = 0; i < 8; ++i) ss += o[i] * o[i];
; #pragma unroll
;             for (int s = 1; s < 32; s <<= 1) ss += __shfl_xor(ss, s);
;             const float rstd = rsqrtf(ss * (1.0f / 256.0f) + EPS);
;             u32x4 w; w.x = pk2(o[0] * rstd, o[1] * rstd); w.y = pk2(o[2] * rstd, o[3] * rstd); w.z = pk2(o[4] * rstd, o[5] * rstd); w.w = pk2(o[6] * rstd, o[7] * rstd);
;             *(u32x4*)(Y + (size_t)(t0 + t) * DM + 768 + c8 * 8) = w;
;         }
; __device__ __forceinline__ void ret_out(const Args& a, int tile, LAS unsigned char* lds, int tid, int lane, int wave) {
;     ...
;     const int b = tile >> 7, n = (tile & 127) >> 1, half = tile & 1, t0 = tile * 64, k0 = b * SEQ + n * 128, fr = lane & 15, fq = lane >> 4;
;     const int cb = wave & 3, hv = wave >> 2;
;     const int cg = half * 64 + cb * 16 + fr;
;     const int nit = half ? 4 : 2;
;     LAS float* red = (LAS float*)(lds + OFF_RED);
;     const int lr = tid >> 4, lc = tid & 15;
;     u32x4 rq[2], rk[4], rv[4], rp[4];
;     ...
;     RET_ISSUE(0);
	v_mul_f32_e32 v25, v7, v25
	v_and_b32_e32 v3, 0xffff0000, v4
	v_lshlrev_b32_e32 v2, 16, v4
	v_and_b32_e32 v19, 0xffff0000, v5
	v_lshlrev_b32_e32 v18, 16, v5
	v_mul_f32_e32 v24, v6, v24
	v_pk_mul_f32 v[4:5], v[8:9], v[16:17]
	v_mul_f32_e32 v16, v25, v25
	v_pk_mul_f32 v[8:9], v[4:5], v[4:5]
	v_fmac_f32_e32 v16, v24, v24
	s_waitcnt lgkmcnt(0)
	v_pk_mul_f32 v[2:3], v[10:11], v[2:3]
	v_add_f32_e32 v8, v8, v16
	v_pk_mul_f32 v[10:11], v[2:3], v[2:3]
	v_add_f32_e32 v8, v9, v8
	v_pk_mul_f32 v[6:7], v[12:13], v[18:19]
	v_add_f32_e32 v8, v10, v8
	v_pk_mul_f32 v[12:13], v[6:7], v[6:7]
	v_add_f32_e32 v8, v11, v8
	v_add_f32_e32 v8, v12, v8
	v_add_f32_e32 v8, v13, v8
	ds_bpermute_b32 v9, v33, v8
	s_waitcnt lgkmcnt(0)
	v_add_f32_e32 v8, v8, v9
	ds_bpermute_b32 v9, v28, v8
	s_waitcnt lgkmcnt(0)
	v_add_f32_e32 v8, v8, v9
	ds_bpermute_b32 v9, v29, v8
	s_waitcnt lgkmcnt(0)
	v_add_f32_e32 v8, v8, v9
	ds_bpermute_b32 v9, v30, v8
	s_waitcnt lgkmcnt(0)
	v_add_f32_e32 v8, v8, v9
	ds_bpermute_b32 v9, v124, v8
	s_waitcnt lgkmcnt(0)
	v_add_f32_e32 v8, v8, v9
	v_fmamk_f32 v8, v8, 0x3b800000, v179
	v_mul_f32_e32 v9, 0x4b800000, v8
	v_cmp_gt_f32_e32 vcc, s33, v8
	s_nop 1
	v_cndmask_b32_e32 v8, v8, v9, vcc
	v_rsq_f32_e32 v10, v8
	v_add_co_u32_e64 v8, s[38:39], s4, v0
	s_lshl_b32 s4, s0, 13
	v_mul_f32_e32 v0, 0x45800000, v10
	v_cndmask_b32_e32 v0, v10, v0, vcc
	v_addc_co_u32_e64 v9, s[38:39], 0, v1, s[38:39]
	v_mul_f32_e32 v1, v24, v0
	v_mul_f32_e32 v2, v2, v0
	v_mul_f32_e32 v3, v3, v0
	v_mul_f32_e32 v10, v25, v0
	v_mul_f32_e32 v4, v4, v0
	v_mul_f32_e32 v5, v5, v0
	v_mul_f32_e32 v6, v6, v0
	v_mul_f32_e32 v7, v7, v0
	v_cvt_pk_bf16_f32 v0, v1, v10
	v_cvt_pk_bf16_f32 v1, v4, v5
	v_cvt_pk_bf16_f32 v2, v2, v3
	v_cvt_pk_bf16_f32 v3, v6, v7
	global_store_dwordx4 v[14:15], v[0:3], off offset:1536
	s_nop 1
	v_mov_b32_e32 v0, v210
	v_mov_b32_e32 v1, v211
	v_mov_b32_e32 v2, v212
	v_mov_b32_e32 v3, v213
	v_add_u32_e32 v8, v32, v23
	ds_read_b128 v[4:7], v8
	ds_read_b128 v[8:11], v8 offset:16
	s_or_b32 s4, s5, s4
	s_bitcmp1_b32 s36, 0
	v_and_b32_e32 v17, 0xffff0000, v0
	v_lshlrev_b32_e32 v16, 16, v0
	v_and_b32_e32 v13, 0xffff0000, v1
	v_lshlrev_b32_e32 v12, 16, v1
	s_waitcnt lgkmcnt(1)
	v_mul_f32_e32 v17, v5, v17
	v_and_b32_e32 v1, 0xffff0000, v2
	v_lshlrev_b32_e32 v0, 16, v2
	v_and_b32_e32 v15, 0xffff0000, v3
	v_lshlrev_b32_e32 v14, 16, v3
	v_mul_f32_e32 v16, v4, v16
	v_pk_mul_f32 v[2:3], v[6:7], v[12:13]
	v_mul_f32_e32 v12, v17, v17
	v_pk_mul_f32 v[6:7], v[2:3], v[2:3]
	v_fmac_f32_e32 v12, v16, v16
	s_waitcnt lgkmcnt(0)
	v_pk_mul_f32 v[0:1], v[8:9], v[0:1]
	v_add_f32_e32 v6, v6, v12
	v_pk_mul_f32 v[8:9], v[0:1], v[0:1]
	v_add_f32_e32 v6, v7, v6
	v_pk_mul_f32 v[4:5], v[10:11], v[14:15]
	v_add_f32_e32 v6, v8, v6
	v_pk_mul_f32 v[10:11], v[4:5], v[4:5]
	v_add_f32_e32 v6, v9, v6
	v_add_f32_e32 v6, v10, v6
	v_add_f32_e32 v6, v11, v6
	ds_bpermute_b32 v7, v33, v6
	s_waitcnt lgkmcnt(0)
	v_add_f32_e32 v6, v6, v7
	ds_bpermute_b32 v7, v28, v6
	s_waitcnt lgkmcnt(0)
	v_add_f32_e32 v6, v6, v7
	ds_bpermute_b32 v7, v29, v6
	s_waitcnt lgkmcnt(0)
	v_add_f32_e32 v6, v6, v7
	ds_bpermute_b32 v7, v30, v6
	s_waitcnt lgkmcnt(0)
	v_add_f32_e32 v8, v6, v7
	ds_bpermute_b32 v9, v124, v8
	v_mov_b64_e32 v[6:7], s[8:9]
	s_waitcnt lgkmcnt(0)
	v_add_f32_e32 v8, v8, v9
	v_fmamk_f32 v8, v8, 0x3b800000, v179
	v_mul_f32_e32 v9, 0x4b800000, v8
	v_cmp_gt_f32_e32 vcc, s33, v8
	s_nop 1
	v_cndmask_b32_e32 v8, v8, v9, vcc
	v_rsq_f32_e32 v8, v8
	s_nop 0
	v_mul_f32_e32 v9, 0x45800000, v8
	v_cndmask_b32_e32 v8, v8, v9, vcc
	v_mul_f32_e32 v2, v2, v8
	v_mul_f32_e32 v3, v3, v8
	v_mul_f32_e32 v9, v16, v8
	v_mul_f32_e32 v10, v17, v8
	v_mul_f32_e32 v11, v0, v8
	v_mul_f32_e32 v12, v1, v8
	v_mul_f32_e32 v4, v4, v8
	v_mul_f32_e32 v5, v5, v8
	v_cvt_pk_bf16_f32 v0, v9, v10
	v_cvt_pk_bf16_f32 v1, v2, v3
	v_cvt_pk_bf16_f32 v2, v11, v12
	v_cvt_pk_bf16_f32 v3, v4, v5
	global_store_dwordx4 v[20:21], v[0:3], off offset:1536
	s_barrier
	s_nop 0
	v_ashrrev_i32_e32 v58, 4, v126
	v_add_u32_e32 v40, s27, v58
	v_add_u32_e32 v41, s4, v58
	v_and_b32_e32 v127, 15, v126
	v_add_u32_e32 v43, 32, v40
	v_add_u32_e32 v42, 32, v41
	v_lshlrev_b32_e32 v144, 4, v127
	v_mad_i64_i32 v[0:1], s[4:5], v40, s84, v[6:7]
	v_mad_i64_i32 v[2:3], s[4:5], v41, s84, v[6:7]
	v_mad_i64_i32 v[4:5], s[4:5], v43, s84, v[6:7]
	v_mad_i64_i32 v[6:7], s[4:5], v42, s84, v[6:7]
	v_lshl_add_u64 v[0:1], v[0:1], 0, v[144:145]
	v_lshl_add_u64 v[2:3], v[2:3], 0, v[144:145]
	v_lshl_add_u64 v[4:5], v[4:5], 0, v[144:145]
	v_lshl_add_u64 v[20:21], v[6:7], 0, v[144:145]
	global_load_dwordx4 v[8:11], v[2:3], off offset:1536
	global_load_dwordx4 v[12:15], v[2:3], off offset:2560
	s_nop 0
	global_load_dwordx4 v[0:3], v[0:1], off offset:512
	s_nop 0
	global_load_dwordx4 v[4:7], v[4:5], off offset:512
	s_nop 0
	global_load_dwordx4 v[16:19], v[20:21], off offset:1536
	s_nop 0
	global_load_dwordx4 v[20:23], v[20:21], off offset:2560
	v_lshlrev_b32_e32 v63, 3, v127
	v_readfirstlane_b32 s6, v126
	s_cselect_b64 s[4:5], -1, 0
	s_cmp_eq_u32 s24, 0
	v_add_u32_e32 v64, 64, v41
	v_lshlrev_b32_e32 v60, 1, v63
	s_cbranch_scc1 .LBB0_1448
	v_mov_b64_e32 v[24:25], s[8:9]
	v_mad_i64_i32 v[24:25], s[28:29], v64, s84, v[24:25]
	v_mov_b32_e32 v61, v145
	v_lshl_add_u64 v[28:29], v[24:25], 0, v[60:61]
	global_load_dwordx4 v[24:27], v[28:29], off offset:1536
	s_nop 0
	global_load_dwordx4 v[28:31], v[28:29], off offset:2560
